# prepR: LoRA weight slices of the block staged once into LDS (swizzled LDS-DMA), MFMAs fed by ds_read_b128 instead of per-wave global loads
# speedup vs baseline: 1.0408x; 1.0157x over previous
; __device__ __forceinline__ void prepR_phase(const Params& P, int wid, int G, int NGW, int lane) {
;     const int fr = lane & 15, fq = lane >> 4; unsigned char* ws = P.ws;
;     const bf16* PR = (const bf16*)(ws + OFF_PR); const bf16* PKR = (const bf16*)(ws + OFF_PKR); const bf16* PVR = (const bf16*)(ws + OFF_PVR); const bf16* PX = (const bf16*)(ws + OFF_PX);
;     const bf16* LW = (const bf16*)(ws + OFF_LW); const bf16* LA = (const bf16*)(ws + OFF_LA); const bf16* LG = (const bf16*)(ws + OFF_LG);
;     h16* SR = (h16*)(ws + OFF_SR); h16* SK = (h16*)(ws + OFF_SK); h16* SKK = (h16*)(ws + OFF_SKK); h16* SB = (h16*)(ws + OFF_SB); h16* SE = (h16*)(ws + OFF_SE); h16* SV = (h16*)(ws + OFF_SV); h16* SG = (h16*)(ws + OFF_SG);
;     float* BON = (float*)(ws + OFF_BONUS);
;     const float* mu = P.in[I_MU];
;     for (int it = wid * G + (int)blockIdx.x; it < (MMAIN / 16) * 2 + 8; it += NGW) {
;         const bool mt = it >= (MMAIN / 16) * 2; const int h0 = mt ? it - (MMAIN / 16) * 2 : 4 * (it & 1), nh = mt ? 1 : 4; const int row_raw = (mt ? MMAIN : 16 * (it >> 1)) + fr; const bool valid = row_raw < MVALID; const int row = valid ? row_raw : 0;
;         const int prow = (row >= MMAIN) ? (row == MMAIN ? -1 : row - 1) : ((row & (SEQ - 1)) == 0 ? MVALID - 1 : row - 1);
;         bf16x8 xwf[2], xaf[2], xgf[4];
; #pragma unroll
.LBB0_739:
	s_cmp_gt_i32 s88, 7
	s_cselect_b64 s[0:1], -1, 0
	s_cmp_lt_i32 s89, 8
	s_cselect_b64 s[2:3], -1, 0
	s_or_b64 s[0:1], s[0:1], s[2:3]
	s_and_b64 vcc, exec, s[0:1]
	s_cbranch_vccnz .LBB0_833
	s_add_i32 s30, s44, s33
	s_cmpk_gt_i32 s30, 0x807
	s_cbranch_scc1 .LBB0_779
	s_and_b32 s0, s33, 1
	s_lshl_b32 s2, s91, 14
	v_lshrrev_b32_e32 v4, 4, v208
	v_lshlrev_b32_e32 v0, 4, v208
	s_cmp_lt_u32 s91, 4
	s_cbranch_scc1 .Lmy_stg_wa
	s_lshl_b32 s3, s0, 16
	s_add_i32 s3, s3, s2
	s_add_i32 s3, s3, 0x2990000
	s_add_u32 s4, s86, s3
	s_addc_u32 s5, s87, 0
	v_and_b32_e32 v4, 3, v4
	v_lshlrev_b32_e32 v4, 4, v4
	v_xor_b32_e32 v0, v0, v4
	v_xor_b32_e32 v1, 64, v0
	v_xor_b32_e32 v2, 0x80, v0
	v_xor_b32_e32 v3, 0xc0, v0
	s_mov_b32 m0, s2
	s_nop 0
	global_load_lds_dwordx4 v0, s[4:5] offset:0
	global_load_lds_dwordx4 v0, s[4:5] offset:1024
	global_load_lds_dwordx4 v0, s[4:5] offset:2048
	global_load_lds_dwordx4 v0, s[4:5] offset:3072
	s_add_u32 s4, s4, 0x1000
	s_addc_u32 s5, s5, 0
	s_add_i32 m0, s2, 0x1000
	s_nop 0
	global_load_lds_dwordx4 v1, s[4:5] offset:0
	global_load_lds_dwordx4 v1, s[4:5] offset:1024
	global_load_lds_dwordx4 v1, s[4:5] offset:2048
	global_load_lds_dwordx4 v1, s[4:5] offset:3072
	s_add_u32 s4, s4, 0x1000
	s_addc_u32 s5, s5, 0
	s_add_i32 m0, s2, 0x2000
	s_nop 0
	global_load_lds_dwordx4 v2, s[4:5] offset:0
	global_load_lds_dwordx4 v2, s[4:5] offset:1024
	global_load_lds_dwordx4 v2, s[4:5] offset:2048
	global_load_lds_dwordx4 v2, s[4:5] offset:3072
	s_add_u32 s4, s4, 0x1000
	s_addc_u32 s5, s5, 0
	s_add_i32 m0, s2, 0x3000
	s_nop 0
	global_load_lds_dwordx4 v3, s[4:5] offset:0
	global_load_lds_dwordx4 v3, s[4:5] offset:1024
	global_load_lds_dwordx4 v3, s[4:5] offset:2048
	global_load_lds_dwordx4 v3, s[4:5] offset:3072
	s_branch .Lmy_stg_done
.Lmy_stg_wa:
	s_lshr_b32 s3, s91, 1
	s_lshl_b32 s3, s3, 16
	s_and_b32 s1, s91, 1
	s_lshl_b32 s1, s1, 14
	s_add_i32 s3, s3, s1
	s_lshl_b32 s1, s0, 15
	s_add_i32 s3, s3, s1
	s_add_i32 s3, s3, 0x2980000
	s_add_u32 s4, s86, s3
	s_addc_u32 s5, s87, 0
	v_and_b32_e32 v4, 1, v4
	v_lshlrev_b32_e32 v4, 4, v4
	v_xor_b32_e32 v0, v0, v4
	v_xor_b32_e32 v1, 32, v0
	v_xor_b32_e32 v2, 64, v0
	v_xor_b32_e32 v3, 0x60, v0
	s_mov_b32 m0, s2
	s_nop 0
	global_load_lds_dwordx4 v0, s[4:5] offset:0
	global_load_lds_dwordx4 v0, s[4:5] offset:1024
	global_load_lds_dwordx4 v1, s[4:5] offset:2048
	global_load_lds_dwordx4 v1, s[4:5] offset:3072
	s_add_u32 s4, s4, 0x1000
	s_addc_u32 s5, s5, 0
	s_add_i32 m0, s2, 0x1000
	s_nop 0
	global_load_lds_dwordx4 v2, s[4:5] offset:0
	global_load_lds_dwordx4 v2, s[4:5] offset:1024
	global_load_lds_dwordx4 v3, s[4:5] offset:2048
	global_load_lds_dwordx4 v3, s[4:5] offset:3072
	s_add_u32 s4, s4, 0x1000
	s_addc_u32 s5, s5, 0
	s_add_i32 m0, s2, 0x2000
	s_nop 0
	global_load_lds_dwordx4 v0, s[4:5] offset:0
	global_load_lds_dwordx4 v0, s[4:5] offset:1024
	global_load_lds_dwordx4 v1, s[4:5] offset:2048
	global_load_lds_dwordx4 v1, s[4:5] offset:3072
	s_add_u32 s4, s4, 0x1000
	s_addc_u32 s5, s5, 0
	s_add_i32 m0, s2, 0x3000
	s_nop 0
	global_load_lds_dwordx4 v2, s[4:5] offset:0
	global_load_lds_dwordx4 v2, s[4:5] offset:1024
	global_load_lds_dwordx4 v3, s[4:5] offset:2048
	global_load_lds_dwordx4 v3, s[4:5] offset:3072
.Lmy_stg_done:
	s_add_u32 s6, s86, 0x7dc0000
	s_addc_u32 s7, s87, 0
	s_add_u32 s8, s86, 0x8e00000
	s_addc_u32 s9, s87, 0
	s_add_u32 s10, s86, 0x9e40000
	s_addc_u32 s11, s87, 0
	s_add_u32 s12, s86, 0xae80000
	s_addc_u32 s13, s87, 0
	s_add_u32 s14, s86, 0xc740000
	s_addc_u32 s15, s87, 0
	s_add_u32 s16, s86, 0xd780000
	s_addc_u32 s17, s87, 0
	s_add_u32 s18, s86, 0xe7c0000
	s_addc_u32 s19, s87, 0
	s_add_u32 s20, s86, 0x4d00000
	v_lshrrev_b32_e32 v0, 1, v209
	s_addc_u32 s21, s87, 0
	v_and_b32_e32 v0, 24, v0
	s_add_u32 s22, s86, 0x5d40000
	v_mov_b32_e32 v143, 0
	v_lshlrev_b32_e32 v142, 1, v0
	s_addc_u32 s23, s87, 0
	s_waitcnt lgkmcnt(0)
	v_lshl_add_u64 v[2:3], s[86:87], 0, v[142:143]
	s_mov_b64 s[2:3], 0x2980000
	s_add_u32 s24, s86, 0x6d80000
	v_lshl_add_u64 v[144:145], v[2:3], 0, s[2:3]
	s_mov_b64 s[2:3], 0x2990000
	s_addc_u32 s25, s87, 0
	v_lshl_add_u64 v[146:147], v[2:3], 0, s[2:3]
	s_mov_b64 s[2:3], 0x29a0000
	s_add_u32 s0, s76, 0x1800
	v_lshl_add_u64 v[148:149], v[2:3], 0, s[2:3]
	v_lshlrev_b32_e32 v2, 2, v0
	s_addc_u32 s1, s77, 0
	v_or_b32_e32 v4, 0x80, v2
	v_mov_b32_e32 v5, v143
	v_lshl_add_u64 v[152:153], s[0:1], 0, v[4:5]
	v_or_b32_e32 v4, 0x100, v2
	v_lshl_add_u64 v[154:155], s[0:1], 0, v[4:5]
	v_or_b32_e32 v4, 0x180, v2
	v_lshl_add_u64 v[156:157], s[0:1], 0, v[4:5]
	v_or_b32_e32 v4, 0x200, v2
	v_mov_b32_e32 v3, v143
	v_lshl_add_u64 v[158:159], s[0:1], 0, v[4:5]
	v_or_b32_e32 v4, 0x280, v2
	v_lshl_add_u64 v[150:151], s[0:1], 0, v[2:3]
	v_lshl_add_u64 v[160:161], s[0:1], 0, v[4:5]
	v_or_b32_e32 v4, 0x300, v2
	v_or_b32_e32 v2, 0x380, v2
	v_lshl_add_u64 v[164:165], s[0:1], 0, v[2:3]
	v_mbcnt_lo_u32_b32 v2, -1, 0
	v_mbcnt_hi_u32_b32 v2, -1, v2
	v_lshl_add_u64 v[162:163], s[0:1], 0, v[4:5]
	v_and_b32_e32 v4, 64, v2
	v_xor_b32_e32 v3, 16, v2
	v_add_u32_e32 v4, 64, v4
	v_cmp_lt_i32_e64 s[0:1], v3, v4
	s_add_u32 s26, s76, 0x1000
	s_addc_u32 s27, s77, 0
	v_cndmask_b32_e64 v3, v2, v3, s[0:1]
	v_lshlrev_b32_e32 v238, 2, v3
	v_xor_b32_e32 v3, 32, v2
	v_cmp_lt_i32_e64 s[0:1], v3, v4
	v_lshlrev_b32_e32 v1, 2, v209
	v_and_b32_e32 v6, 3, v209
	v_cndmask_b32_e64 v2, v2, v3, s[0:1]
	s_add_u32 s31, s86, 0x2ac0000
	v_and_b32_e32 v236, 15, v209
	v_and_b32_e32 v237, 48, v209
	v_cmp_gt_u32_e32 vcc, 16, v208
	v_lshlrev_b32_e32 v239, 2, v2
	v_lshl_add_u64 v[166:167], s[12:13], 0, v[142:143]
	s_addc_u32 s34, s87, 0
	v_and_or_b32 v240, v1, 48, v6
	s_movk_i32 s35, 0x4000
	s_mov_b32 s36, 0xbfb8aa3b
	s_mov_b32 s37, 0x800000
	s_mov_b32 s38, 0x3f317217
	s_mov_b32 s39, 0x7f800000
	v_mov_b32_e32 v241, 0x400f
	v_lshlrev_b32_e32 v168, 1, v0
	v_mov_b32_e32 v242, 0x41b17218
	s_branch .LBB0_743

; __device__ __forceinline__ unsigned pk2(float lo, float hi) { return pg8::cvt_pk_bf16(lo, hi); }
; __device__ __forceinline__ void prepR_phase(const Params& P, int wid, int G, int NGW, int lane) {
;     ...
;         for (int ks = 0; ks < 8; ++ks) {
;             const int col = 32 * ks + 8 * fq; float p[8], pp[8]; ld8(PX + (size_t)row * 256 + col, true, p); ld8(PX + (size_t)(prow < 0 ? 0 : prow) * 256 + col, prow >= 0, pp);
;             const f32x4 m0 = *(const f32x4*)(mu + 1536 + col), m1 = *(const f32x4*)(mu + 1536 + col + 4); float x[8];
; #pragma unroll
;             for (int e = 0; e < 8; ++e) { const float m = e < 4 ? m0[e & 3] : m1[e & 3]; x[e] = p[e] + (pp[e] - p[e]) * m; }
;             if (ks < 2) {
; #pragma unroll
;                 for (int e = 0; e < 8; ++e) { const float t = __expf(-2.0f * __builtin_fabsf(x[e])); const float th = (1.0f - t) * __builtin_amdgcn_rcpf(1.0f + t); x[e] = x[e] < 0.f ? -th : th; }
;             } else if (ks >= 4) {
; #pragma unroll
;                 for (int e = 0; e < 8; ++e) x[e] = __builtin_amdgcn_rcpf(1.0f + __expf(-x[e]));
;             }
;             const u32x4 w = (u32x4){pk2(x[0], x[1]), pk2(x[2], x[3]), pk2(x[4], x[5]), pk2(x[6], x[7])};
;             const bf16x8 f = __builtin_bit_cast(bf16x8, w);
;             if (ks < 2) xwf[ks] = f; else if (ks < 4) xaf[ks - 2] = f; else xgf[ks - 4] = f;
;         }
.LBB0_763:
	s_or_b64 exec, exec, s[0:1]
	s_waitcnt vmcnt(0)
	v_lshlrev_b32_e32 v122, 16, v112
	v_and_b32_e32 v112, 0xffff0000, v112
	v_lshlrev_b32_e32 v126, 16, v108
	v_and_b32_e32 v108, 0xffff0000, v108
	v_lshlrev_b32_e32 v123, 16, v113
	v_lshlrev_b32_e32 v127, 16, v109
	v_sub_f32_e32 v108, v108, v112
	v_and_b32_e32 v113, 0xffff0000, v113
	v_and_b32_e32 v109, 0xffff0000, v109
	v_fmac_f32_e32 v112, v117, v108
	v_sub_f32_e32 v108, v127, v123
	v_lshlrev_b32_e32 v124, 16, v114
	v_lshlrev_b32_e32 v128, 16, v110
	v_fmac_f32_e32 v123, v118, v108
	v_sub_f32_e32 v108, v109, v113
	v_lshlrev_b32_e32 v125, 16, v115
	v_lshlrev_b32_e32 v129, 16, v111
	v_fmac_f32_e32 v113, v119, v108
	v_sub_f32_e32 v108, v128, v124
	v_and_b32_e32 v115, 0xffff0000, v115
	v_and_b32_e32 v111, 0xffff0000, v111
	v_fmac_f32_e32 v124, v0, v108
	v_sub_f32_e32 v108, v129, v125
	v_fmac_f32_e32 v125, v2, v108
	v_sub_f32_e32 v2, v111, v115
	v_fmac_f32_e32 v115, v3, v2
	v_mul_f32_e32 v2, 0xbfb8aa3b, v115
	v_exp_f32_e32 v2, v2
	v_mul_f32_e32 v3, 0xbfb8aa3b, v125
	v_and_b32_e32 v114, 0xffff0000, v114
	v_and_b32_e32 v110, 0xffff0000, v110
	v_exp_f32_e32 v3, v3
	v_sub_f32_e32 v0, v110, v114
	v_fmac_f32_e32 v114, v1, v0
	v_add_f32_e32 v0, 1.0, v2
	v_mul_f32_e32 v1, 0xbfb8aa3b, v114
	v_rcp_f32_e32 v108, v0
	v_add_f32_e32 v0, 1.0, v3
	v_exp_f32_e32 v1, v1
	v_mul_f32_e32 v2, 0xbfb8aa3b, v124
	v_mul_f32_e32 v3, 0xbfb8aa3b, v113
	v_exp_f32_e32 v2, v2
	v_exp_f32_e32 v3, v3
	v_add_f32_e32 v1, 1.0, v1
	v_rcp_f32_e32 v109, v1
	v_add_f32_e32 v1, 1.0, v2
	v_add_f32_e32 v2, 1.0, v3
	v_mul_f32_e32 v3, 0xbfb8aa3b, v123
	v_exp_f32_e32 v3, v3
	v_rcp_f32_e32 v2, v2
	v_mul_f32_e32 v110, 0xbfb8aa3b, v112
	v_rcp_f32_e32 v112, v1
	v_add_f32_e32 v3, 1.0, v3
	v_rcp_f32_e32 v3, v3
	v_rcp_f32_e32 v113, v0
	v_sub_f32_e32 v126, v126, v122
	v_fmac_f32_e32 v122, v116, v126
	v_cvt_pk_bf16_f32 v1, v3, v2
	v_cvt_pk_bf16_f32 v2, v112, v109
	v_lshlrev_b32_e32 v112, 16, v96
	v_and_b32_e32 v96, 0xffff0000, v96
	v_lshlrev_b32_e32 v116, 16, v4
	v_and_b32_e32 v4, 0xffff0000, v4
	v_cvt_pk_bf16_f32 v3, v113, v108
	v_lshlrev_b32_e32 v113, 16, v97
	v_lshlrev_b32_e32 v117, 16, v5
	v_sub_f32_e32 v4, v4, v96
	v_and_b32_e32 v97, 0xffff0000, v97
	v_lshlrev_b32_e32 v115, 16, v99
	v_and_b32_e32 v5, 0xffff0000, v5
	v_lshlrev_b32_e32 v119, 16, v7
	v_fmac_f32_e32 v96, v101, v4
	v_sub_f32_e32 v4, v117, v113
	v_and_b32_e32 v99, 0xffff0000, v99
	v_and_b32_e32 v7, 0xffff0000, v7
	v_fmac_f32_e32 v113, v102, v4
	v_sub_f32_e32 v4, v5, v97
	v_sub_f32_e32 v5, v119, v115
	v_fmac_f32_e32 v115, v94, v5
	v_sub_f32_e32 v5, v7, v99
	v_lshlrev_b32_e32 v114, 16, v98
	v_lshlrev_b32_e32 v118, 16, v6
	v_fmac_f32_e32 v99, v95, v5
	v_and_b32_e32 v98, 0xffff0000, v98
	v_and_b32_e32 v6, 0xffff0000, v6
	v_fmac_f32_e32 v97, v103, v4
	v_sub_f32_e32 v4, v118, v114
	v_mul_f32_e32 v5, 0xbfb8aa3b, v99
	v_fmac_f32_e32 v114, v92, v4
	v_sub_f32_e32 v4, v6, v98
	v_exp_f32_e32 v5, v5
	v_mul_f32_e32 v6, 0xbfb8aa3b, v115
	v_exp_f32_e32 v6, v6
	v_fmac_f32_e32 v98, v93, v4
	v_add_f32_e32 v4, 1.0, v5
	v_mul_f32_e32 v5, 0xbfb8aa3b, v98
	v_rcp_f32_e32 v7, v4
	v_add_f32_e32 v4, 1.0, v6
	v_exp_f32_e32 v5, v5
	v_mul_f32_e32 v6, 0xbfb8aa3b, v114
	v_mul_f32_e32 v92, 0xbfb8aa3b, v97
	v_exp_f32_e32 v6, v6
	v_exp_f32_e32 v92, v92
	v_add_f32_e32 v5, 1.0, v5
	v_rcp_f32_e32 v93, v5
	v_add_f32_e32 v5, 1.0, v6
	v_add_f32_e32 v6, 1.0, v92
	v_mul_f32_e32 v92, 0xbfb8aa3b, v113
	v_sub_f32_e32 v116, v116, v112
	v_exp_f32_e32 v92, v92
	v_fmac_f32_e32 v112, v100, v116
	v_mul_f32_e32 v94, 0xbfb8aa3b, v96
	v_mul_f32_e32 v95, 0xbfb8aa3b, v112
	v_exp_f32_e32 v94, v94
	v_exp_f32_e32 v95, v95
	v_add_f32_e32 v92, 1.0, v92
	v_rcp_f32_e32 v6, v6
	v_rcp_f32_e32 v92, v92
	v_rcp_f32_e32 v96, v5
	v_rcp_f32_e32 v97, v4
	v_add_f32_e32 v94, 1.0, v94
	v_add_f32_e32 v95, 1.0, v95
	v_rcp_f32_e32 v94, v94
	v_rcp_f32_e32 v95, v95
	v_cvt_pk_bf16_f32 v5, v92, v6
	v_cvt_pk_bf16_f32 v6, v96, v93
	v_lshlrev_b32_e32 v92, 16, v84
	v_and_b32_e32 v84, 0xffff0000, v84
	v_lshlrev_b32_e32 v96, 16, v80
	v_and_b32_e32 v80, 0xffff0000, v80
	v_cvt_pk_bf16_f32 v7, v97, v7
	v_lshlrev_b32_e32 v93, 16, v85
	v_lshlrev_b32_e32 v97, 16, v81
	v_sub_f32_e32 v80, v80, v84
	v_and_b32_e32 v85, 0xffff0000, v85
	v_and_b32_e32 v81, 0xffff0000, v81
	v_fmac_f32_e32 v84, v89, v80
	v_sub_f32_e32 v80, v97, v93
	v_cvt_pk_bf16_f32 v4, v95, v94
	v_lshlrev_b32_e32 v94, 16, v86
	v_lshlrev_b32_e32 v98, 16, v82
	v_fmac_f32_e32 v93, v90, v80
	v_sub_f32_e32 v80, v81, v85
	v_lshlrev_b32_e32 v95, 16, v87
	v_lshlrev_b32_e32 v99, 16, v83
	v_fmac_f32_e32 v85, v91, v80
	v_sub_f32_e32 v80, v98, v94
	v_and_b32_e32 v87, 0xffff0000, v87
	v_and_b32_e32 v83, 0xffff0000, v83
	v_fmac_f32_e32 v94, v8, v80
	v_sub_f32_e32 v80, v99, v95
	v_fmac_f32_e32 v95, v10, v80
	v_sub_f32_e32 v10, v83, v87
	v_fmac_f32_e32 v87, v11, v10
	v_mul_f32_e32 v10, 0xbfb8aa3b, v87
	v_exp_f32_e32 v10, v10
	v_mul_f32_e32 v11, 0xbfb8aa3b, v95
	v_and_b32_e32 v86, 0xffff0000, v86
	v_and_b32_e32 v82, 0xffff0000, v82
	v_exp_f32_e32 v11, v11
	v_sub_f32_e32 v8, v82, v86
	v_fmac_f32_e32 v86, v9, v8
	v_add_f32_e32 v8, 1.0, v10
	v_mul_f32_e32 v9, 0xbfb8aa3b, v86
	v_rcp_f32_e32 v80, v8
	v_add_f32_e32 v8, 1.0, v11
	v_exp_f32_e32 v9, v9
	v_mul_f32_e32 v10, 0xbfb8aa3b, v94
	v_mul_f32_e32 v11, 0xbfb8aa3b, v85
	v_exp_f32_e32 v10, v10
	v_exp_f32_e32 v11, v11
	v_add_f32_e32 v9, 1.0, v9
	v_sub_f32_e32 v96, v96, v92
	v_rcp_f32_e32 v81, v9
	v_add_f32_e32 v9, 1.0, v10
	v_add_f32_e32 v10, 1.0, v11
	v_mul_f32_e32 v11, 0xbfb8aa3b, v93
	v_fmac_f32_e32 v92, v88, v96
	v_exp_f32_e32 v11, v11
	v_mul_f32_e32 v82, 0xbfb8aa3b, v84
	v_mul_f32_e32 v83, 0xbfb8aa3b, v92
	v_exp_f32_e32 v82, v82
	v_exp_f32_e32 v83, v83
	v_add_f32_e32 v11, 1.0, v11
; __device__ __forceinline__ unsigned pk2(float lo, float hi) { return pg8::cvt_pk_bf16(lo, hi); }
; __device__ __forceinline__ void prepR_phase(const Params& P, int wid, int G, int NGW, int lane) {
;     ...
;         for (int ks = 0; ks < 8; ++ks) {
;             const int col = 32 * ks + 8 * fq; float p[8], pp[8]; ld8(PX + (size_t)row * 256 + col, true, p); ld8(PX + (size_t)(prow < 0 ? 0 : prow) * 256 + col, prow >= 0, pp);
;             const f32x4 m0 = *(const f32x4*)(mu + 1536 + col), m1 = *(const f32x4*)(mu + 1536 + col + 4); float x[8];
; #pragma unroll
;             for (int e = 0; e < 8; ++e) { const float m = e < 4 ? m0[e & 3] : m1[e & 3]; x[e] = p[e] + (pp[e] - p[e]) * m; }
;             if (ks < 2) {
; #pragma unroll
;                 for (int e = 0; e < 8; ++e) { const float t = __expf(-2.0f * __builtin_fabsf(x[e])); const float th = (1.0f - t) * __builtin_amdgcn_rcpf(1.0f + t); x[e] = x[e] < 0.f ? -th : th; }
;             } else if (ks >= 4) {
; #pragma unroll
;                 for (int e = 0; e < 8; ++e) x[e] = __builtin_amdgcn_rcpf(1.0f + __expf(-x[e]));
;             }
;             const u32x4 w = (u32x4){pk2(x[0], x[1]), pk2(x[2], x[3]), pk2(x[4], x[5]), pk2(x[6], x[7])};
;             const bf16x8 f = __builtin_bit_cast(bf16x8, w);
;             if (ks < 2) xwf[ks] = f; else if (ks < 4) xaf[ks - 2] = f; else xgf[ks - 4] = f;
;         }
	v_rcp_f32_e32 v10, v10
	v_rcp_f32_e32 v11, v11
	v_rcp_f32_e32 v84, v9
	v_rcp_f32_e32 v85, v8
	v_add_f32_e32 v82, 1.0, v82
	v_add_f32_e32 v83, 1.0, v83
	v_rcp_f32_e32 v82, v82
	v_rcp_f32_e32 v83, v83
	v_cvt_pk_bf16_f32 v9, v11, v10
	v_cvt_pk_bf16_f32 v10, v84, v81
	v_cvt_pk_bf16_f32 v11, v85, v80
	v_lshlrev_b32_e32 v80, 16, v72
	v_and_b32_e32 v81, 0xffff0000, v72
	v_lshlrev_b32_e32 v72, 16, v73
	v_and_b32_e32 v73, 0xffff0000, v73
	v_lshlrev_b32_e32 v84, 16, v12
	v_and_b32_e32 v85, 0xffff0000, v12
	v_lshlrev_b32_e32 v12, 16, v13
	v_and_b32_e32 v13, 0xffff0000, v13
	v_pk_add_f32 v[12:13], v[12:13], v[72:73] neg_lo:[0,1] neg_hi:[0,1]
	v_cvt_pk_bf16_f32 v8, v83, v82
	v_lshlrev_b32_e32 v82, 16, v74
	v_and_b32_e32 v83, 0xffff0000, v74
	v_pk_fma_f32 v[72:73], v[78:79], v[12:13], v[72:73]
	v_lshlrev_b32_e32 v12, 16, v14
	v_and_b32_e32 v13, 0xffff0000, v14
	v_pk_add_f32 v[12:13], v[12:13], v[82:83] neg_lo:[0,1] neg_hi:[0,1]
	v_lshlrev_b32_e32 v74, 16, v75
	v_and_b32_e32 v75, 0xffff0000, v75
	v_pk_fma_f32 v[68:69], v[68:69], v[12:13], v[82:83]
	v_lshlrev_b32_e32 v12, 16, v15
	v_and_b32_e32 v13, 0xffff0000, v15
	v_pk_add_f32 v[12:13], v[12:13], v[74:75] neg_lo:[0,1] neg_hi:[0,1]
	v_cvt_pk_bf16_f32 v14, v68, v69
	v_pk_fma_f32 v[70:71], v[70:71], v[12:13], v[74:75]
	v_cvt_pk_bf16_f32 v13, v72, v73
	v_lshlrev_b32_e32 v68, 16, v60
	v_and_b32_e32 v69, 0xffff0000, v60
	v_lshlrev_b32_e32 v60, 16, v61
	v_and_b32_e32 v61, 0xffff0000, v61
	v_lshlrev_b32_e32 v72, 16, v16
	v_and_b32_e32 v73, 0xffff0000, v16
	v_lshlrev_b32_e32 v16, 16, v17
	v_and_b32_e32 v17, 0xffff0000, v17
	v_pk_add_f32 v[16:17], v[16:17], v[60:61] neg_lo:[0,1] neg_hi:[0,1]
	v_cvt_pk_bf16_f32 v15, v70, v71
	v_lshlrev_b32_e32 v70, 16, v62
	v_and_b32_e32 v71, 0xffff0000, v62
	v_pk_fma_f32 v[60:61], v[66:67], v[16:17], v[60:61]
	v_lshlrev_b32_e32 v16, 16, v18
	v_and_b32_e32 v17, 0xffff0000, v18
	v_pk_add_f32 v[16:17], v[16:17], v[70:71] neg_lo:[0,1] neg_hi:[0,1]
	v_lshlrev_b32_e32 v62, 16, v63
	v_and_b32_e32 v63, 0xffff0000, v63
	v_pk_fma_f32 v[56:57], v[56:57], v[16:17], v[70:71]
	v_lshlrev_b32_e32 v16, 16, v19
	v_and_b32_e32 v17, 0xffff0000, v19
	v_pk_add_f32 v[16:17], v[16:17], v[62:63] neg_lo:[0,1] neg_hi:[0,1]
	v_cvt_pk_bf16_f32 v18, v56, v57
	v_pk_fma_f32 v[58:59], v[58:59], v[16:17], v[62:63]
	v_cvt_pk_bf16_f32 v17, v60, v61
	v_cvt_pk_bf16_f32 v19, v58, v59
	v_lshlrev_b32_e32 v58, 16, v51
	v_and_b32_e32 v59, 0xffff0000, v51
	v_lshlrev_b32_e32 v60, 16, v23
	v_and_b32_e32 v61, 0xffff0000, v23
	v_pk_add_f32 v[60:61], v[60:61], v[58:59] neg_lo:[0,1] neg_hi:[0,1]
	v_lshlrev_b32_e32 v62, 16, v50
	v_pk_fma_f32 v[54:55], v[54:55], v[60:61], v[58:59]
	v_and_b32_e32 v63, 0xffff0000, v50
	v_mul_f32_e64 v23, |v55|, -2.0
	v_mul_f32_e32 v23, 0x3fb8aa3b, v23
	v_exp_f32_e32 v59, v23
	v_mul_f32_e64 v23, |v54|, -2.0
	v_mul_f32_e32 v23, 0x3fb8aa3b, v23
	v_exp_f32_e32 v58, v23
	v_add_f32_e32 v23, 1.0, v59
	v_rcp_f32_e32 v61, v23
	v_cmp_gt_f32_e64 s[0:1], 0, v55
	v_add_f32_e32 v23, 1.0, v58
	v_pk_add_f32 v[50:51], v[58:59], 1.0 op_sel_hi:[1,0] neg_lo:[1,0] neg_hi:[1,0]
	v_lshlrev_b32_e32 v58, 16, v22
	v_and_b32_e32 v59, 0xffff0000, v22
	v_rcp_f32_e32 v60, v23
	v_pk_add_f32 v[22:23], v[58:59], v[62:63] neg_lo:[0,1] neg_hi:[0,1]
	v_lshlrev_b32_e32 v56, 16, v48
	v_pk_fma_f32 v[22:23], v[52:53], v[22:23], v[62:63]
	v_pk_mul_f32 v[50:51], v[50:51], v[60:61]
	v_mul_f32_e64 v52, |v23|, -2.0
	v_mul_f32_e32 v52, 0x3fb8aa3b, v52
	v_exp_f32_e32 v53, v52
	v_mul_f32_e64 v52, |v22|, -2.0
	v_mul_f32_e32 v52, 0x3fb8aa3b, v52
	v_exp_f32_e32 v52, v52
	v_cndmask_b32_e64 v55, v51, -v51, s[0:1]
	v_add_f32_e32 v51, 1.0, v53
	v_rcp_f32_e32 v59, v51
	v_add_f32_e32 v51, 1.0, v52
	v_cmp_gt_f32_e64 s[0:1], 0, v54
	v_and_b32_e32 v57, 0xffff0000, v48
	v_lshlrev_b32_e32 v48, 16, v49
	v_and_b32_e32 v49, 0xffff0000, v49
	v_rcp_f32_e32 v58, v51
	v_cndmask_b32_e64 v54, v50, -v50, s[0:1]
	v_pk_add_f32 v[50:51], v[52:53], 1.0 op_sel_hi:[1,0] neg_lo:[1,0] neg_hi:[1,0]
	v_lshlrev_b32_e32 v52, 16, v21
	v_and_b32_e32 v53, 0xffff0000, v21
	v_pk_add_f32 v[52:53], v[52:53], v[48:49] neg_lo:[0,1] neg_hi:[0,1]
	v_pk_mul_f32 v[50:51], v[50:51], v[58:59]
	v_pk_fma_f32 v[46:47], v[46:47], v[52:53], v[48:49]
	v_cmp_gt_f32_e64 s[0:1], 0, v23
	v_mul_f32_e64 v21, |v47|, -2.0
	v_mul_f32_e32 v21, 0x3fb8aa3b, v21
	v_exp_f32_e32 v49, v21
	v_mul_f32_e64 v21, |v46|, -2.0
	v_mul_f32_e32 v21, 0x3fb8aa3b, v21
	v_exp_f32_e32 v48, v21
	v_add_f32_e32 v21, 1.0, v49
	v_cndmask_b32_e64 v51, v51, -v51, s[0:1]
	v_rcp_f32_e32 v53, v21
	v_add_f32_e32 v21, 1.0, v48
	v_cmp_gt_f32_e64 s[0:1], 0, v22
	v_pk_add_f32 v[22:23], v[48:49], 1.0 op_sel_hi:[1,0] neg_lo:[1,0] neg_hi:[1,0]
	v_lshlrev_b32_e32 v48, 16, v20
	v_and_b32_e32 v49, 0xffff0000, v20
	v_rcp_f32_e32 v52, v21
	v_pk_add_f32 v[20:21], v[48:49], v[56:57] neg_lo:[0,1] neg_hi:[0,1]
	v_cndmask_b32_e64 v50, v50, -v50, s[0:1]
	v_pk_fma_f32 v[20:21], v[44:45], v[20:21], v[56:57]
	v_pk_mul_f32 v[22:23], v[22:23], v[52:53]
	v_mul_f32_e64 v44, |v21|, -2.0
	v_mul_f32_e32 v44, 0x3fb8aa3b, v44
	v_exp_f32_e32 v45, v44
	v_mul_f32_e64 v44, |v20|, -2.0
	v_mul_f32_e32 v44, 0x3fb8aa3b, v44
	v_exp_f32_e32 v44, v44
	v_cmp_gt_f32_e64 s[0:1], 0, v47
	v_mul_f32_e32 v111, 0xbfb8aa3b, v122
	v_exp_f32_e32 v110, v110
	v_cndmask_b32_e64 v47, v23, -v23, s[0:1]
	v_add_f32_e32 v23, 1.0, v45
	v_rcp_f32_e32 v49, v23
	v_add_f32_e32 v23, 1.0, v44
	v_rcp_f32_e32 v48, v23
	v_cmp_gt_f32_e64 s[0:1], 0, v46
	v_exp_f32_e32 v111, v111
	v_add_f32_e32 v110, 1.0, v110
	v_cndmask_b32_e64 v46, v22, -v22, s[0:1]
	v_pk_add_f32 v[22:23], v[44:45], 1.0 op_sel_hi:[1,0] neg_lo:[1,0] neg_hi:[1,0]
	v_cmp_gt_f32_e64 s[0:1], 0, v21
	v_pk_mul_f32 v[22:23], v[22:23], v[48:49]
; __device__ __forceinline__ unsigned pk2(float lo, float hi) { return pg8::cvt_pk_bf16(lo, hi); }
; __device__ __forceinline__ void prepR_phase(const Params& P, int wid, int G, int NGW, int lane) {
;     ...
;         for (int ks = 0; ks < 8; ++ks) {
;             const int col = 32 * ks + 8 * fq; float p[8], pp[8]; ld8(PX + (size_t)row * 256 + col, true, p); ld8(PX + (size_t)(prow < 0 ? 0 : prow) * 256 + col, prow >= 0, pp);
;             const f32x4 m0 = *(const f32x4*)(mu + 1536 + col), m1 = *(const f32x4*)(mu + 1536 + col + 4); float x[8];
; #pragma unroll
;             for (int e = 0; e < 8; ++e) { const float m = e < 4 ? m0[e & 3] : m1[e & 3]; x[e] = p[e] + (pp[e] - p[e]) * m; }
;             if (ks < 2) {
; #pragma unroll
;                 for (int e = 0; e < 8; ++e) { const float t = __expf(-2.0f * __builtin_fabsf(x[e])); const float th = (1.0f - t) * __builtin_amdgcn_rcpf(1.0f + t); x[e] = x[e] < 0.f ? -th : th; }
;             } else if (ks >= 4) {
; #pragma unroll
;                 for (int e = 0; e < 8; ++e) x[e] = __builtin_amdgcn_rcpf(1.0f + __expf(-x[e]));
;             }
;             const u32x4 w = (u32x4){pk2(x[0], x[1]), pk2(x[2], x[3]), pk2(x[4], x[5]), pk2(x[6], x[7])};
;             const bf16x8 f = __builtin_bit_cast(bf16x8, w);
;             if (ks < 2) xwf[ks] = f; else if (ks < 4) xaf[ks - 2] = f; else xgf[ks - 4] = f;
;         }
	v_lshlrev_b32_e32 v48, 16, v35
	v_cndmask_b32_e64 v21, v23, -v23, s[0:1]
	v_cmp_gt_f32_e64 s[0:1], 0, v20
	v_and_b32_e32 v49, 0xffff0000, v35
	v_lshlrev_b32_e32 v44, 16, v32
	v_cndmask_b32_e64 v20, v22, -v22, s[0:1]
	v_cvt_pk_bf16_f32 v22, v50, v51
	v_lshlrev_b32_e32 v50, 16, v27
	v_and_b32_e32 v51, 0xffff0000, v27
	v_pk_add_f32 v[50:51], v[50:51], v[48:49] neg_lo:[0,1] neg_hi:[0,1]
	v_cvt_pk_bf16_f32 v20, v20, v21
	v_pk_fma_f32 v[48:49], v[42:43], v[50:51], v[48:49]
	v_cvt_pk_bf16_f32 v21, v46, v47
	v_mul_f32_e64 v27, |v49|, -2.0
	v_mul_f32_e32 v27, 0x3fb8aa3b, v27
	v_exp_f32_e32 v43, v27
	v_mul_f32_e64 v27, |v48|, -2.0
	v_mul_f32_e32 v27, 0x3fb8aa3b, v27
	v_exp_f32_e32 v42, v27
	v_add_f32_e32 v27, 1.0, v43
	v_lshlrev_b32_e32 v46, 16, v33
	v_and_b32_e32 v47, 0xffff0000, v33
	v_rcp_f32_e32 v33, v27
	v_add_f32_e32 v27, 1.0, v42
	v_and_b32_e32 v45, 0xffff0000, v32
	v_rcp_f32_e32 v32, v27
	v_lshlrev_b32_e32 v50, 16, v34
	v_and_b32_e32 v51, 0xffff0000, v34
	v_pk_add_f32 v[34:35], v[42:43], 1.0 op_sel_hi:[1,0] neg_lo:[1,0] neg_hi:[1,0]
	v_cmp_gt_f32_e64 s[0:1], 0, v49
	v_pk_mul_f32 v[52:53], v[34:35], v[32:33]
	v_lshlrev_b32_e32 v32, 16, v26
	v_and_b32_e32 v33, 0xffff0000, v26
	v_pk_add_f32 v[26:27], v[32:33], v[50:51] neg_lo:[0,1] neg_hi:[0,1]
	v_cvt_pk_bf16_f32 v23, v54, v55
	v_pk_fma_f32 v[26:27], v[40:41], v[26:27], v[50:51]
	global_load_dwordx4 v[32:35], v[164:165], off offset:16
	global_load_dwordx4 v[40:43], v[164:165], off
	v_mul_f32_e64 v50, |v27|, -2.0
	v_mul_f32_e32 v50, 0x3fb8aa3b, v50
	v_exp_f32_e32 v51, v50
	v_mul_f32_e64 v50, |v26|, -2.0
	v_mul_f32_e32 v50, 0x3fb8aa3b, v50
	v_exp_f32_e32 v50, v50
	v_add_f32_e32 v49, 1.0, v51
	v_rcp_f32_e32 v55, v49
	v_cndmask_b32_e64 v53, v53, -v53, s[0:1]
	v_add_f32_e32 v49, 1.0, v50
	v_rcp_f32_e32 v54, v49
	v_cmp_gt_f32_e64 s[0:1], 0, v48
	v_pk_add_f32 v[48:49], v[50:51], 1.0 op_sel_hi:[1,0] neg_lo:[1,0] neg_hi:[1,0]
	v_lshlrev_b32_e32 v50, 16, v25
	v_and_b32_e32 v51, 0xffff0000, v25
	v_pk_add_f32 v[50:51], v[50:51], v[46:47] neg_lo:[0,1] neg_hi:[0,1]
	v_cndmask_b32_e64 v52, v52, -v52, s[0:1]
	v_pk_fma_f32 v[30:31], v[30:31], v[50:51], v[46:47]
	v_pk_mul_f32 v[48:49], v[48:49], v[54:55]
	v_mul_f32_e64 v25, |v31|, -2.0
	v_mul_f32_e32 v25, 0x3fb8aa3b, v25
	v_exp_f32_e32 v47, v25
	v_mul_f32_e64 v25, |v30|, -2.0
	v_mul_f32_e32 v25, 0x3fb8aa3b, v25
	v_exp_f32_e32 v46, v25
	v_cmp_gt_f32_e64 s[0:1], 0, v27
	v_add_f32_e32 v25, 1.0, v47
	v_rcp_f32_e32 v51, v25
	v_cndmask_b32_e64 v49, v49, -v49, s[0:1]
	v_add_f32_e32 v25, 1.0, v46
	v_cmp_gt_f32_e64 s[0:1], 0, v26
	v_pk_add_f32 v[26:27], v[46:47], 1.0 op_sel_hi:[1,0] neg_lo:[1,0] neg_hi:[1,0]
	v_lshlrev_b32_e32 v46, 16, v24
	v_and_b32_e32 v47, 0xffff0000, v24
	v_rcp_f32_e32 v50, v25
	v_pk_add_f32 v[24:25], v[46:47], v[44:45] neg_lo:[0,1] neg_hi:[0,1]
	v_cndmask_b32_e64 v48, v48, -v48, s[0:1]
	v_pk_fma_f32 v[24:25], v[28:29], v[24:25], v[44:45]
	v_pk_mul_f32 v[26:27], v[26:27], v[50:51]
	v_mul_f32_e64 v28, |v25|, -2.0
	v_mul_f32_e32 v28, 0x3fb8aa3b, v28
	v_exp_f32_e32 v29, v28
	v_mul_f32_e64 v28, |v24|, -2.0
	v_mul_f32_e32 v28, 0x3fb8aa3b, v28
	v_exp_f32_e32 v28, v28
	v_cmp_gt_f32_e64 s[0:1], 0, v31
	v_add_f32_e32 v111, 1.0, v111
	v_rcp_f32_e32 v110, v110
	v_cndmask_b32_e64 v31, v27, -v27, s[0:1]
	v_add_f32_e32 v27, 1.0, v29
	v_rcp_f32_e32 v45, v27
	v_add_f32_e32 v27, 1.0, v28
	v_rcp_f32_e32 v44, v27
	v_cmp_gt_f32_e64 s[0:1], 0, v30
	v_rcp_f32_e32 v111, v111
	v_lshlrev_b32_e32 v108, 16, v104
	v_cndmask_b32_e64 v30, v26, -v26, s[0:1]
	v_pk_add_f32 v[26:27], v[28:29], 1.0 op_sel_hi:[1,0] neg_lo:[1,0] neg_hi:[1,0]
	v_cmp_gt_f32_e64 s[0:1], 0, v25
	v_pk_mul_f32 v[26:27], v[26:27], v[44:45]
	v_lshlrev_b32_e32 v28, 16, v36
	v_cndmask_b32_e64 v25, v27, -v27, s[0:1]
	v_cmp_gt_f32_e64 s[0:1], 0, v24
	v_cvt_pk_bf16_f32 v0, v111, v110
	v_and_b32_e32 v104, 0xffff0000, v104
	v_cndmask_b32_e64 v24, v26, -v26, s[0:1]
	v_lshlrev_b32_e32 v111, 16, v107
	v_cvt_pk_bf16_f32 v24, v24, v25
	v_cvt_pk_bf16_f32 v25, v30, v31
	v_and_b32_e32 v29, 0xffff0000, v36
	v_lshlrev_b32_e32 v30, 16, v37
	v_and_b32_e32 v31, 0xffff0000, v37
	v_lshlrev_b32_e32 v36, 16, v38
	v_and_b32_e32 v37, 0xffff0000, v38
	v_lshlrev_b32_e32 v38, 16, v39
	v_sub_f32_e32 v28, v28, v108
	v_and_b32_e32 v107, 0xffff0000, v107
	v_and_b32_e32 v39, 0xffff0000, v39
	v_lshlrev_b32_e32 v109, 16, v105
	s_waitcnt vmcnt(0)
; __device__ __forceinline__ unsigned pk2(float lo, float hi) { return pg8::cvt_pk_bf16(lo, hi); }
; __device__ __forceinline__ void prepR_phase(const Params& P, int wid, int G, int NGW, int lane) {
;     ...
;         const bool mt = it >= (MMAIN / 16) * 2; const int h0 = mt ? it - (MMAIN / 16) * 2 : 4 * (it & 1), nh = mt ? 1 : 4; const int row_raw = (mt ? MMAIN : 16 * (it >> 1)) + fr; const bool valid = row_raw < MVALID; const int row = valid ? row_raw : 0;
;         const int prow = (row >= MMAIN) ? (row == MMAIN ? -1 : row - 1) : ((row & (SEQ - 1)) == 0 ? MVALID - 1 : row - 1);
;         bf16x8 xwf[2], xaf[2], xgf[4];
; #pragma unroll
;         for (int ks = 0; ks < 8; ++ks) {
;             const int col = 32 * ks + 8 * fq; float p[8], pp[8]; ld8(PX + (size_t)row * 256 + col, true, p); ld8(PX + (size_t)(prow < 0 ? 0 : prow) * 256 + col, prow >= 0, pp);
;             const f32x4 m0 = *(const f32x4*)(mu + 1536 + col), m1 = *(const f32x4*)(mu + 1536 + col + 4); float x[8];
; #pragma unroll
;             for (int e = 0; e < 8; ++e) { const float m = e < 4 ? m0[e & 3] : m1[e & 3]; x[e] = p[e] + (pp[e] - p[e]) * m; }
;             if (ks < 2) {
; #pragma unroll
;                 for (int e = 0; e < 8; ++e) { const float t = __expf(-2.0f * __builtin_fabsf(x[e])); const float th = (1.0f - t) * __builtin_amdgcn_rcpf(1.0f + t); x[e] = x[e] < 0.f ? -th : th; }
;             } else if (ks >= 4) {
; #pragma unroll
;                 for (int e = 0; e < 8; ++e) x[e] = __builtin_amdgcn_rcpf(1.0f + __expf(-x[e]));
;             }
;             const u32x4 w = (u32x4){pk2(x[0], x[1]), pk2(x[2], x[3]), pk2(x[4], x[5]), pk2(x[6], x[7])};
;             const bf16x8 f = __builtin_bit_cast(bf16x8, w);
;             if (ks < 2) xwf[ks] = f; else if (ks < 4) xaf[ks - 2] = f; else xgf[ks - 4] = f;
;         }
	v_fmac_f32_e32 v108, v40, v28
	v_sub_f32_e32 v28, v29, v104
	v_sub_f32_e32 v29, v38, v111
	v_fmac_f32_e32 v111, v34, v29
	v_sub_f32_e32 v29, v39, v107
	v_fmac_f32_e32 v107, v35, v29
	v_and_b32_e32 v105, 0xffff0000, v105
	v_fmac_f32_e32 v104, v41, v28
	v_sub_f32_e32 v28, v30, v109
	v_mul_f32_e32 v29, 0xbfb8aa3b, v107
	v_lshlrev_b32_e32 v110, 16, v106
	v_fmac_f32_e32 v109, v42, v28
	v_sub_f32_e32 v28, v31, v105
	v_exp_f32_e32 v29, v29
	v_mul_f32_e32 v30, 0xbfb8aa3b, v111
	v_and_b32_e32 v106, 0xffff0000, v106
	v_fmac_f32_e32 v105, v43, v28
	v_sub_f32_e32 v28, v36, v110
	v_exp_f32_e32 v30, v30
	v_fmac_f32_e32 v110, v32, v28
	v_sub_f32_e32 v28, v37, v106
	v_fmac_f32_e32 v106, v33, v28
	v_add_f32_e32 v28, 1.0, v29
	v_mul_f32_e32 v29, 0xbfb8aa3b, v106
	v_rcp_f32_e32 v31, v28
	v_add_f32_e32 v28, 1.0, v30
	v_exp_f32_e32 v29, v29
	v_mul_f32_e32 v30, 0xbfb8aa3b, v110
	v_mul_f32_e32 v32, 0xbfb8aa3b, v105
	v_exp_f32_e32 v30, v30
	v_exp_f32_e32 v32, v32
	v_add_f32_e32 v29, 1.0, v29
	v_rcp_f32_e32 v33, v29
	v_add_f32_e32 v29, 1.0, v30
	v_add_f32_e32 v30, 1.0, v32
	v_mul_f32_e32 v32, 0xbfb8aa3b, v109
	v_exp_f32_e32 v32, v32
	v_mul_f32_e32 v34, 0xbfb8aa3b, v104
	v_mul_f32_e32 v35, 0xbfb8aa3b, v108
	v_exp_f32_e32 v34, v34
	v_exp_f32_e32 v35, v35
	s_lshl_b32 s0, s30, 2
	v_add_f32_e32 v32, 1.0, v32
	s_add_i32 s28, s30, 0xfffff800
	s_and_b32 s29, s0, 4
	v_rcp_f32_e32 v30, v30
	v_rcp_f32_e32 v32, v32
	v_rcp_f32_e32 v36, v29
	s_and_b64 s[0:1], s[4:5], exec
	s_cselect_b32 s28, s28, s29
	v_add_f32_e32 v34, 1.0, v34
	v_add_f32_e32 v35, 1.0, v35
	s_cselect_b32 s0, 1, 4
	s_mov_b32 s101, s0
	v_rcp_f32_e32 v34, v34
	v_rcp_f32_e32 v35, v35
	v_rcp_f32_e32 v37, v28
	s_ashr_i32 s29, s28, 31
	v_cvt_pk_bf16_f32 v29, v32, v30
	v_cvt_pk_bf16_f32 v30, v36, v33
	s_add_i32 s56, s28, s0
	v_lshlrev_b64 v[32:33], 1, v[170:171]
	v_max_i32_e32 v142, 0, v142
	s_lshl_b64 s[0:1], s[28:29], 2
	v_pk_add_f32 v[84:85], v[84:85], v[80:81] neg_lo:[0,1] neg_hi:[0,1]
	v_pk_add_f32 v[72:73], v[72:73], v[68:69] neg_lo:[0,1] neg_hi:[0,1]
	v_lshl_add_u64 v[172:173], s[6:7], 0, v[32:33]
	v_lshl_add_u64 v[174:175], s[8:9], 0, v[32:33]
	v_lshl_add_u64 v[176:177], s[10:11], 0, v[32:33]
	v_lshlrev_b64 v[32:33], 10, v[142:143]
	s_add_u32 s0, s31, s0
	v_pk_fma_f32 v[76:77], v[76:77], v[84:85], v[80:81]
	v_pk_fma_f32 v[64:65], v[64:65], v[72:73], v[68:69]
	v_lshl_add_u64 v[178:179], s[6:7], 0, v[32:33]
	v_lshl_add_u64 v[180:181], s[8:9], 0, v[32:33]
	v_lshl_add_u64 v[182:183], s[10:11], 0, v[32:33]
	v_lshlrev_b64 v[32:33], 5, v[120:121]
	s_addc_u32 s1, s34, s1
	v_cvt_pk_bf16_f32 v12, v76, v77
	v_cvt_pk_bf16_f32 v16, v64, v65
	v_cvt_pk_bf16_f32 v26, v48, v49
	v_cvt_pk_bf16_f32 v27, v52, v53
	v_cvt_pk_bf16_f32 v28, v35, v34
	v_cvt_pk_bf16_f32 v31, v37, v31
	v_lshl_add_u64 v[184:185], s[0:1], 0, v[32:33]
	s_lshl_b32 s29, s28, 6
	s_cmp_eq_u32 s101, 1
	s_cbranch_scc1 .Lmy_lora_nobar
	s_waitcnt vmcnt(0)
	s_barrier
.Lmy_lora_nobar:
	s_branch .LBB0_765

; __device__ __forceinline__ void prepR_phase(const Params& P, int wid, int G, int NGW, int lane) {
;     ...
;         for (int h = h0; h < h0 + nh; ++h) {
;             f32x4 wacc[4], aacc[4], gacc[4];
; #pragma unroll
;             for (int nt = 0; nt < 4; ++nt) {
;                 wacc[nt] = (f32x4){0.f, 0.f, 0.f, 0.f}; aacc[nt] = wacc[nt]; gacc[nt] = wacc[nt];
;                 const int chr = h * 64 + 16 * (fr >> 2) + 4 * nt + (fr & 3);
; #pragma unroll
;                 for (int ks = 0; ks < 2; ++ks) {
;                     const bf16x8 bw = *(const bf16x8*)(LW + (size_t)chr * 64 + 32 * ks + 8 * fq), ba = *(const bf16x8*)(LA + (size_t)chr * 64 + 32 * ks + 8 * fq);
;                     wacc[nt] = __builtin_amdgcn_mfma_f32_16x16x32_bf16(bw, xwf[ks], wacc[nt], 0, 0, 0);
;                     aacc[nt] = __builtin_amdgcn_mfma_f32_16x16x32_bf16(ba, xaf[ks], aacc[nt], 0, 0, 0);
;                 }
; #pragma unroll
;                 for (int ks = 0; ks < 4; ++ks) {
;                     const bf16x8 bg = *(const bf16x8*)(LG + (size_t)chr * 128 + 32 * ks + 8 * fq);
;                     gacc[nt] = __builtin_amdgcn_mfma_f32_16x16x32_bf16(bg, xgf[ks], gacc[nt], 0, 0, 0);
;                 }
;             }
.LBB0_765:
	s_cmp_eq_u32 s101, 1
	s_cbranch_scc1 .Lmy_lora_meta
	v_add_u32_e32 v188, s29, v237
	s_and_b32 s0, s33, 1
	s_lshl_b32 s0, s0, 8
	s_sub_i32 s0, s29, s0
	v_ashrrev_i32_e32 v189, 31, v188
	v_add_u32_e32 v88, s0, v240
	v_lshlrev_b32_e32 v89, 3, v236
	v_lshl_add_u64 v[210:211], v[188:189], 1, v[172:173]
	v_and_b32_e32 v89, 0x70, v89
	v_lshlrev_b32_e32 v104, 4, v236
	global_load_dwordx4 v[56:59], v[210:211], off
	v_xor_b32_e32 v89, v237, v89
	v_xor_b32_e32 v104, v237, v104
	v_lshl_add_u32 v102, v88, 7, v89
	v_lshl_add_u32 v88, v88, 8, v104
	v_xor_b32_e32 v103, 64, v102
	v_add_u32_e32 v88, 0x10000, v88
	v_lshl_add_u64 v[214:215], v[188:189], 1, v[178:179]
	v_xor_b32_e32 v104, 64, v88
	v_xor_b32_e32 v105, 0x80, v88
	v_xor_b32_e32 v89, 0xc0, v88
	ds_read_b128 v[60:63], v102 offset:0
	ds_read_b128 v[64:67], v102 offset:512
	ds_read_b128 v[68:71], v102 offset:1024
	ds_read_b128 v[72:75], v102 offset:1536
	ds_read_b128 v[76:79], v102 offset:32768
	ds_read_b128 v[80:83], v102 offset:33280
	ds_read_b128 v[84:87], v102 offset:33792
	ds_read_b128 v[118:121], v102 offset:34304
	s_waitcnt lgkmcnt(7)
	v_mfma_f32_16x16x32_bf16 v[114:117], v[60:63], v[24:27], 0
	ds_read_b128 v[60:63], v88 offset:0
	s_waitcnt lgkmcnt(7)
	v_mfma_f32_16x16x32_bf16 v[106:109], v[64:67], v[24:27], 0
	ds_read_b128 v[64:67], v88 offset:1024
	s_waitcnt lgkmcnt(7)
	v_mfma_f32_16x16x32_bf16 v[52:55], v[68:71], v[24:27], 0
	ds_read_b128 v[68:71], v88 offset:2048
	s_waitcnt lgkmcnt(7)
	v_mfma_f32_16x16x32_bf16 v[44:47], v[72:75], v[24:27], 0
	ds_read_b128 v[72:75], v88 offset:3072
	s_waitcnt lgkmcnt(7)
	v_mfma_f32_16x16x32_bf16 v[110:113], v[76:79], v[16:19], 0
	ds_read_b128 v[76:79], v103 offset:0
	s_waitcnt lgkmcnt(7)
	v_mfma_f32_16x16x32_bf16 v[98:101], v[80:83], v[16:19], 0
	ds_read_b128 v[80:83], v103 offset:512
	s_waitcnt lgkmcnt(7)
	v_mfma_f32_16x16x32_bf16 v[48:51], v[84:87], v[16:19], 0
	ds_read_b128 v[84:87], v103 offset:1024
	s_waitcnt lgkmcnt(7)
	v_mfma_f32_16x16x32_bf16 v[40:43], v[118:121], v[16:19], 0
	ds_read_b128 v[118:121], v103 offset:1536
	s_waitcnt lgkmcnt(7)
	v_mfma_f32_16x16x32_bf16 v[90:93], v[60:63], v[8:11], 0
	ds_read_b128 v[60:63], v103 offset:32768
	s_waitcnt lgkmcnt(7)
	v_mfma_f32_16x16x32_bf16 v[94:97], v[64:67], v[8:11], 0
	ds_read_b128 v[64:67], v103 offset:33280
	s_waitcnt lgkmcnt(7)
	v_mfma_f32_16x16x32_bf16 v[32:35], v[68:71], v[8:11], 0
	ds_read_b128 v[68:71], v103 offset:33792
	s_waitcnt lgkmcnt(7)
	v_mfma_f32_16x16x32_bf16 v[36:39], v[72:75], v[8:11], 0
	ds_read_b128 v[72:75], v103 offset:34304
	s_waitcnt lgkmcnt(7)
	v_mfma_f32_16x16x32_bf16 v[114:117], v[76:79], v[20:23], v[114:117]
	ds_read_b128 v[76:79], v104 offset:0
	s_waitcnt lgkmcnt(7)
	v_mfma_f32_16x16x32_bf16 v[106:109], v[80:83], v[20:23], v[106:109]
	ds_read_b128 v[80:83], v104 offset:1024
	s_waitcnt lgkmcnt(7)
	v_mfma_f32_16x16x32_bf16 v[52:55], v[84:87], v[20:23], v[52:55]
	ds_read_b128 v[84:87], v104 offset:2048
	s_waitcnt lgkmcnt(7)
	v_mfma_f32_16x16x32_bf16 v[44:47], v[118:121], v[20:23], v[44:47]
	ds_read_b128 v[118:121], v104 offset:3072
	s_waitcnt lgkmcnt(7)
	v_mfma_f32_16x16x32_bf16 v[110:113], v[60:63], v[12:15], v[110:113]
	ds_read_b128 v[60:63], v105 offset:0
	s_waitcnt lgkmcnt(7)
	v_mfma_f32_16x16x32_bf16 v[98:101], v[64:67], v[12:15], v[98:101]
	ds_read_b128 v[64:67], v105 offset:1024
	s_waitcnt lgkmcnt(7)
	v_mfma_f32_16x16x32_bf16 v[48:51], v[68:71], v[12:15], v[48:51]
	ds_read_b128 v[68:71], v105 offset:2048
	s_waitcnt lgkmcnt(7)
	v_mfma_f32_16x16x32_bf16 v[40:43], v[72:75], v[12:15], v[40:43]
	ds_read_b128 v[72:75], v105 offset:3072
	s_waitcnt lgkmcnt(7)
	v_mfma_f32_16x16x32_bf16 v[90:93], v[76:79], v[4:7], v[90:93]
	ds_read_b128 v[76:79], v89 offset:0
	s_waitcnt lgkmcnt(7)
	v_mfma_f32_16x16x32_bf16 v[94:97], v[80:83], v[4:7], v[94:97]
	ds_read_b128 v[80:83], v89 offset:1024
	s_waitcnt lgkmcnt(7)
	v_mfma_f32_16x16x32_bf16 v[32:35], v[84:87], v[4:7], v[32:35]
	ds_read_b128 v[84:87], v89 offset:2048
	s_waitcnt lgkmcnt(7)
	v_mfma_f32_16x16x32_bf16 v[36:39], v[118:121], v[4:7], v[36:39]
	ds_read_b128 v[118:121], v89 offset:3072
	s_waitcnt lgkmcnt(7)
	v_mfma_f32_16x16x32_bf16 v[90:93], v[60:63], v[0:3], v[90:93]
	s_waitcnt lgkmcnt(6)
	v_mfma_f32_16x16x32_bf16 v[94:97], v[64:67], v[0:3], v[94:97]
	s_waitcnt lgkmcnt(5)
	v_mfma_f32_16x16x32_bf16 v[32:35], v[68:71], v[0:3], v[32:35]
	s_waitcnt lgkmcnt(4)
	v_mfma_f32_16x16x32_bf16 v[36:39], v[72:75], v[0:3], v[36:39]
	s_waitcnt lgkmcnt(3)
	v_mfma_f32_16x16x32_bf16 v[90:93], v[76:79], v[28:31], v[90:93]
	s_waitcnt lgkmcnt(2)
	v_mfma_f32_16x16x32_bf16 v[94:97], v[80:83], v[28:31], v[94:97]
	s_waitcnt lgkmcnt(1)
	v_mfma_f32_16x16x32_bf16 v[32:35], v[84:87], v[28:31], v[32:35]
	s_waitcnt lgkmcnt(0)
	v_mfma_f32_16x16x32_bf16 v[36:39], v[118:121], v[28:31], v[36:39]
	s_nop 7
	v_mov_b32_e32 v72, 0
	v_mov_b32_e32 v60, 0
	v_mov_b32_e32 v61, 0
	v_mov_b32_e32 v62, 0
	v_mov_b32_e32 v63, 0
	s_nop 7
	s_waitcnt vmcnt(0)
	s_branch .Lmy_lora_join

; __device__ __forceinline__ void prepR_phase(const Params& P, int wid, int G, int NGW, int lane) {
;     ...
;                 const int col = col16 + 8 * hf; float r8[8], k8[8], v8[8], pp[8];
;                 { ld8(PR + (size_t)row * 512 + col, true, r8); ld8(PR + (size_t)(prow < 0 ? 0 : prow) * 512 + col, prow >= 0, pp); const f32x4 m0 = *(const f32x4*)(mu + col), m1 = *(const f32x4*)(mu + col + 4);
.Lmy_lora_join:
	s_and_saveexec_b64 s[0:1], s[2:3]
	s_cbranch_execz .LBB0_767
	global_load_dwordx4 v[60:63], v[214:215], off
